# P8 epilogue: wave owns 64 consecutive output columns (B LDS read remap) + DPP half-row exchange so every nt store writes full 128B lines
# speedup vs baseline: 1.0117x; 1.0027x over previous
.LBB0_1716:
	s_add_u32 s51, s78, 0x4000000
	s_addc_u32 s52, s79, 0
	s_lshl_b32 s6, s6, 5
	s_and_b32 s12, s6, 0x60
	s_mov_b64 s[6:7], 0x80
	s_add_i32 m0, s29, 0x18000
	v_lshl_add_u64 v[6:7], v[6:7], 0, s[6:7]
	s_ashr_i32 s53, s33, 31
	s_lshl_b32 s9, s8, 13
	s_lshl_b32 s13, s12, 7
	s_waitcnt vmcnt(2)
	s_barrier
	global_load_lds_dwordx4 v[6:7], off
	v_lshl_add_u64 v[4:5], v[4:5], 0, s[6:7]
	s_add_i32 m0, s29, 0x1a000
	s_add_i32 s54, s29, 0x8000
	s_add_i32 s55, s29, 0xa000
	global_load_lds_dwordx4 v[4:5], off
	v_lshl_add_u64 v[0:1], v[0:1], 0, s[6:7]
	s_mov_b32 m0, s54
	s_add_u32 s10, s40, 0x40080
	global_load_lds_dwordx4 v[0:1], off
	v_lshl_add_u64 v[0:1], v[2:3], 0, s[6:7]
	s_mov_b32 m0, s55
	s_addc_u32 s11, s41, 0
	global_load_lds_dwordx4 v[0:1], off
	s_add_i32 m0, s29, 0x1c000
	v_lshl_add_u64 v[0:1], s[10:11], 0, v[132:133]
	global_load_lds_dwordx4 v[0:1], off
	v_lshl_add_u64 v[0:1], s[10:11], 0, v[128:129]
	s_add_i32 m0, s29, 0x1e000
	s_cmpk_lt_u32 s1, 0x100
	global_load_lds_dwordx4 v[0:1], off
	v_lshrrev_b32_e32 v1, 1, v9
	v_and_b32_e32 v1, 24, v1
	v_and_b32_e32 v0, 15, v9
	v_lshlrev_b32_e32 v2, 1, v1
	v_lshl_or_b32 v146, s8, 6, v0
	v_and_b32_e32 v146, -9, v146
	v_lshl_or_b32 v0, v0, 6, v2
	v_lshlrev_b32_e32 v2, 2, v9
	v_and_b32_e32 v2, 32, v2
	v_bitop3_b32 v3, v0, s9, v2 bitop3:0xde
	v_bitop3_b32 v147, v0, s13, v2 bitop3:0xde
	v_add_u32_e32 v147, s13, v147
	v_lshlrev_b32_e32 v0, 14, v13
	v_and_b32_e32 v0, 0xffff8000, v0
	v_or_b32_e32 v148, s12, v1
	v_add_u32_e32 v148, s12, v148
	v_and_b32_e32 v227, 8, v9
	v_lshl_add_u32 v148, v227, 2, v148
	s_mov_b64 s[98:99], 0x10000
	v_lshl_add_u32 v0, v12, 11, v0
	v_and_b32_e32 v1, 1, v13
	v_lshl_or_b32 v0, v1, 6, v0
	v_lshl_add_u32 v136, v14, 1, v0
	v_lshlrev_b32_e32 v0, 14, v8
	v_and_b32_e32 v0, 0xffff8000, v0
	s_waitcnt vmcnt(6)
	v_lshl_add_u32 v0, v10, 11, v0
	v_and_b32_e32 v1, 1, v8
	s_cselect_b64 s[8:9], -1, 0
	v_lshl_or_b32 v0, v1, 6, v0
	s_add_i32 s56, 0, 0x10000
	s_add_i32 s57, 0, 0x14000
	s_sext_i32_i16 s62, s0
	v_mov_b32_e32 v137, v133
	v_lshl_add_u32 v138, v11, 1, v0
	v_mov_b32_e32 v139, v133
	v_mov_b64_e32 v[140:141], 0x800
	v_mov_b64_e32 v[142:143], 0x7ff
	v_add_u32_e32 v149, s56, v147
	v_add_u32_e32 v150, 0x11000, v147
	v_add_u32_e32 v151, 0, v3
	s_mov_b64 s[10:11], 0x100000
	s_mov_b32 s58, 0x100000
	s_mov_b64 s[12:13], 0x120000
	s_mov_b32 s59, 0x120000
	s_mov_b64 s[14:15], 0x140000
	s_mov_b32 s60, 0x140000
	s_mov_b64 s[16:17], 0x160000
	s_mov_b32 s61, 0x160000
	s_barrier
	s_branch .LBB0_1719

.LBB0_1726:
	ds_read_b128 v[152:155], v149
	ds_read_b128 v[156:159], v149 offset:1024
	ds_read_b128 v[160:163], v149 offset:2048
	ds_read_b128 v[164:167], v149 offset:3072
	ds_read_b128 v[168:171], v150
	ds_read_b128 v[172:175], v150 offset:1024
	ds_read_b128 v[176:179], v150 offset:2048
	ds_read_b128 v[180:183], v150 offset:3072
	s_add_u32 s40, s30, 0xfffc0080
	s_addc_u32 s41, s31, -1
	s_cmp_eq_u32 s67, 12
	s_cselect_b32 s43, s21, s41
	s_cselect_b32 s42, s63, s40
	s_cselect_b32 s41, s19, s66
	s_cselect_b32 s40, s64, s65
	v_lshl_add_u64 v[144:145], s[30:31], 0, v[136:137]
	s_add_i32 m0, s29, 0xc000
	ds_read_b128 v[184:187], v151
	ds_read_b128 v[188:191], v151 offset:1024
	ds_read_b128 v[192:195], v151 offset:2048
	ds_read_b128 v[196:199], v151 offset:3072
	ds_read_b128 v[200:203], v151 offset:4096
	ds_read_b128 v[204:207], v151 offset:5120
	ds_read_b128 v[208:211], v151 offset:6144
	ds_read_b128 v[212:215], v151 offset:7168
	global_load_lds_dwordx4 v[144:145], off
	v_lshl_add_u64 v[144:145], s[30:31], 0, v[138:139]
	s_add_i32 m0, s29, 0xe000
	s_nop 0
	global_load_lds_dwordx4 v[144:145], off
	s_waitcnt vmcnt(8)
	s_waitcnt lgkmcnt(0)
	s_barrier
	s_setprio 1
	s_waitcnt lgkmcnt(0)
	v_mfma_f32_16x16x32_bf16 v[124:127], v[152:155], v[184:187], v[124:127]
	v_mfma_f32_16x16x32_bf16 v[120:123], v[160:163], v[184:187], v[120:123]
	v_mfma_f32_16x16x32_bf16 v[116:119], v[152:155], v[192:195], v[116:119]
	v_mfma_f32_16x16x32_bf16 v[108:111], v[160:163], v[192:195], v[108:111]
	v_mfma_f32_16x16x32_bf16 v[100:103], v[152:155], v[200:203], v[100:103]
	v_mfma_f32_16x16x32_bf16 v[92:95], v[160:163], v[200:203], v[92:95]
	v_mfma_f32_16x16x32_bf16 v[84:87], v[152:155], v[208:211], v[84:87]
	v_mfma_f32_16x16x32_bf16 v[76:79], v[160:163], v[208:211], v[76:79]
	v_mfma_f32_16x16x32_bf16 v[124:127], v[156:159], v[188:191], v[124:127]
	v_mfma_f32_16x16x32_bf16 v[120:123], v[164:167], v[188:191], v[120:123]
	v_mfma_f32_16x16x32_bf16 v[116:119], v[156:159], v[196:199], v[116:119]
	v_mfma_f32_16x16x32_bf16 v[108:111], v[164:167], v[196:199], v[108:111]
	v_mfma_f32_16x16x32_bf16 v[100:103], v[156:159], v[204:207], v[100:103]
	v_mfma_f32_16x16x32_bf16 v[92:95], v[164:167], v[204:207], v[92:95]
	v_mfma_f32_16x16x32_bf16 v[84:87], v[156:159], v[212:215], v[84:87]
	v_mfma_f32_16x16x32_bf16 v[76:79], v[164:167], v[212:215], v[76:79]
	s_setprio 0
	s_setprio 1
	v_mfma_f32_16x16x32_bf16 v[112:115], v[168:171], v[184:187], v[112:115]
	v_mfma_f32_16x16x32_bf16 v[104:107], v[176:179], v[184:187], v[104:107]
	v_mfma_f32_16x16x32_bf16 v[96:99], v[168:171], v[192:195], v[96:99]
	v_mfma_f32_16x16x32_bf16 v[88:91], v[176:179], v[192:195], v[88:91]
	v_mfma_f32_16x16x32_bf16 v[80:83], v[168:171], v[200:203], v[80:83]
	v_mfma_f32_16x16x32_bf16 v[72:75], v[176:179], v[200:203], v[72:75]
	v_mfma_f32_16x16x32_bf16 v[68:71], v[168:171], v[208:211], v[68:71]
	v_mfma_f32_16x16x32_bf16 v[64:67], v[176:179], v[208:211], v[64:67]
	v_mfma_f32_16x16x32_bf16 v[112:115], v[172:175], v[188:191], v[112:115]
	v_mfma_f32_16x16x32_bf16 v[104:107], v[180:183], v[188:191], v[104:107]
	v_mfma_f32_16x16x32_bf16 v[96:99], v[172:175], v[196:199], v[96:99]
	v_mfma_f32_16x16x32_bf16 v[88:91], v[180:183], v[196:199], v[88:91]
	v_mfma_f32_16x16x32_bf16 v[80:83], v[172:175], v[204:207], v[80:83]
	v_mfma_f32_16x16x32_bf16 v[72:75], v[180:183], v[204:207], v[72:75]
	v_mfma_f32_16x16x32_bf16 v[68:71], v[172:175], v[212:215], v[68:71]
	v_mfma_f32_16x16x32_bf16 v[64:67], v[180:183], v[212:215], v[64:67]
	s_setprio 0
	s_barrier
	s_add_i32 s68, s56, s45
	v_lshl_add_u64 v[144:145], s[40:41], 0, v[132:133]
	s_mov_b32 m0, s68
	ds_read_b128 v[184:187], v151 offset:16384
	ds_read_b128 v[188:191], v151 offset:17408
	ds_read_b128 v[192:195], v151 offset:18432
	ds_read_b128 v[196:199], v151 offset:19456
	ds_read_b128 v[200:203], v151 offset:20480
	ds_read_b128 v[204:207], v151 offset:21504
	ds_read_b128 v[208:211], v151 offset:22528
	ds_read_b128 v[212:215], v151 offset:23552
	global_load_lds_dwordx4 v[144:145], off
	s_add_i32 m0, s68, 0x2000
	s_add_u32 s68, s40, 0x40000
	v_lshl_add_u64 v[216:217], s[40:41], 0, v[128:129]
	s_addc_u32 s69, s41, 0
	s_add_i32 s72, s57, s45
	global_load_lds_dwordx4 v[216:217], off
	v_lshl_add_u64 v[218:219], s[68:69], 0, v[132:133]
	s_mov_b32 m0, s72
	v_lshl_add_u64 v[220:221], s[42:43], 0, v[130:131]
	global_load_lds_dwordx4 v[218:219], off
	v_lshl_add_u64 v[218:219], s[68:69], 0, v[128:129]
	s_add_i32 m0, s72, 0x2000
	s_nop 0
	global_load_lds_dwordx4 v[218:219], off
	v_lshl_add_u64 v[218:219], s[42:43], 0, v[134:135]
	s_mov_b32 m0, s29
	s_nop 0
	global_load_lds_dwordx4 v[218:219], off
	s_mov_b32 m0, s47
	s_nop 0
	global_load_lds_dwordx4 v[220:221], off
	s_waitcnt vmcnt(8)
	s_waitcnt lgkmcnt(0)
	s_barrier
	s_setprio 1
	s_waitcnt lgkmcnt(0)
	v_mfma_f32_16x16x32_bf16 v[60:63], v[152:155], v[184:187], v[60:63]
	v_mfma_f32_16x16x32_bf16 v[56:59], v[160:163], v[184:187], v[56:59]
	v_mfma_f32_16x16x32_bf16 v[52:55], v[152:155], v[192:195], v[52:55]
	v_mfma_f32_16x16x32_bf16 v[44:47], v[160:163], v[192:195], v[44:47]
	v_mfma_f32_16x16x32_bf16 v[36:39], v[152:155], v[200:203], v[36:39]
	v_mfma_f32_16x16x32_bf16 v[28:31], v[160:163], v[200:203], v[28:31]
	v_mfma_f32_16x16x32_bf16 v[20:23], v[152:155], v[208:211], v[20:23]
	v_mfma_f32_16x16x32_bf16 v[12:15], v[160:163], v[208:211], v[12:15]
	v_mfma_f32_16x16x32_bf16 v[60:63], v[156:159], v[188:191], v[60:63]
	v_mfma_f32_16x16x32_bf16 v[56:59], v[164:167], v[188:191], v[56:59]
	v_mfma_f32_16x16x32_bf16 v[52:55], v[156:159], v[196:199], v[52:55]
	v_mfma_f32_16x16x32_bf16 v[44:47], v[164:167], v[196:199], v[44:47]
	v_mfma_f32_16x16x32_bf16 v[36:39], v[156:159], v[204:207], v[36:39]
	v_mfma_f32_16x16x32_bf16 v[28:31], v[164:167], v[204:207], v[28:31]
	v_mfma_f32_16x16x32_bf16 v[20:23], v[156:159], v[212:215], v[20:23]
	v_mfma_f32_16x16x32_bf16 v[12:15], v[164:167], v[212:215], v[12:15]
	s_setprio 0
	s_setprio 1
	v_mfma_f32_16x16x32_bf16 v[48:51], v[168:171], v[184:187], v[48:51]
	v_mfma_f32_16x16x32_bf16 v[40:43], v[176:179], v[184:187], v[40:43]
	v_mfma_f32_16x16x32_bf16 v[32:35], v[168:171], v[192:195], v[32:35]
	v_mfma_f32_16x16x32_bf16 v[24:27], v[176:179], v[192:195], v[24:27]
	v_mfma_f32_16x16x32_bf16 v[16:19], v[168:171], v[200:203], v[16:19]
	v_mfma_f32_16x16x32_bf16 v[8:11], v[176:179], v[200:203], v[8:11]
	v_mfma_f32_16x16x32_bf16 v[4:7], v[168:171], v[208:211], v[4:7]
	v_mfma_f32_16x16x32_bf16 v[0:3], v[176:179], v[208:211], v[0:3]
	v_mfma_f32_16x16x32_bf16 v[48:51], v[172:175], v[188:191], v[48:51]
	v_mfma_f32_16x16x32_bf16 v[40:43], v[180:183], v[188:191], v[40:43]
	v_mfma_f32_16x16x32_bf16 v[32:35], v[172:175], v[196:199], v[32:35]
	v_mfma_f32_16x16x32_bf16 v[24:27], v[180:183], v[196:199], v[24:27]
	v_mfma_f32_16x16x32_bf16 v[16:19], v[172:175], v[204:207], v[16:19]
	v_mfma_f32_16x16x32_bf16 v[8:11], v[180:183], v[204:207], v[8:11]
	v_mfma_f32_16x16x32_bf16 v[4:7], v[172:175], v[212:215], v[4:7]
	v_mfma_f32_16x16x32_bf16 v[0:3], v[180:183], v[212:215], v[0:3]
	s_setprio 0
	s_barrier
	s_add_i32 s68, 0, 0x18000
	s_add_i32 s69, 0, 0x1c000
	v_add_u32_e32 v164, s68, v147
	v_add_u32_e32 v180, 0x19000, v147
	ds_read_b128 v[152:155], v164
	ds_read_b128 v[156:159], v164 offset:1024
	ds_read_b128 v[160:163], v164 offset:2048
	ds_read_b128 v[164:167], v164 offset:3072
	ds_read_b128 v[168:171], v180
	ds_read_b128 v[172:175], v180 offset:1024
	ds_read_b128 v[176:179], v180 offset:2048
	ds_read_b128 v[180:183], v180 offset:3072
	s_add_u32 s42, s42, 0x40000
	s_addc_u32 s43, s43, 0
	s_mov_b32 m0, s48
	v_lshl_add_u64 v[222:223], s[42:43], 0, v[134:135]
	ds_read_b128 v[184:187], v151 offset:32768
	ds_read_b128 v[188:191], v151 offset:33792
	ds_read_b128 v[192:195], v151 offset:34816
	ds_read_b128 v[196:199], v151 offset:35840
	ds_read_b128 v[200:203], v151 offset:36864
	ds_read_b128 v[204:207], v151 offset:37888
	ds_read_b128 v[208:211], v151 offset:38912
	ds_read_b128 v[212:215], v151 offset:39936
	global_load_lds_dwordx4 v[222:223], off
	v_lshl_add_u64 v[222:223], s[42:43], 0, v[130:131]
	s_mov_b32 m0, s49
	s_nop 0
	global_load_lds_dwordx4 v[222:223], off
	s_waitcnt vmcnt(8)
	s_waitcnt lgkmcnt(0)
	s_barrier
	s_setprio 1
	s_waitcnt lgkmcnt(0)
	v_mfma_f32_16x16x32_bf16 v[124:127], v[152:155], v[184:187], v[124:127]
	v_mfma_f32_16x16x32_bf16 v[120:123], v[160:163], v[184:187], v[120:123]
	v_mfma_f32_16x16x32_bf16 v[116:119], v[152:155], v[192:195], v[116:119]
	v_mfma_f32_16x16x32_bf16 v[108:111], v[160:163], v[192:195], v[108:111]
	v_mfma_f32_16x16x32_bf16 v[100:103], v[152:155], v[200:203], v[100:103]
	v_mfma_f32_16x16x32_bf16 v[92:95], v[160:163], v[200:203], v[92:95]
	v_mfma_f32_16x16x32_bf16 v[84:87], v[152:155], v[208:211], v[84:87]
	v_mfma_f32_16x16x32_bf16 v[76:79], v[160:163], v[208:211], v[76:79]
	v_mfma_f32_16x16x32_bf16 v[124:127], v[156:159], v[188:191], v[124:127]
	v_mfma_f32_16x16x32_bf16 v[120:123], v[164:167], v[188:191], v[120:123]
	v_mfma_f32_16x16x32_bf16 v[116:119], v[156:159], v[196:199], v[116:119]
	v_mfma_f32_16x16x32_bf16 v[108:111], v[164:167], v[196:199], v[108:111]
	v_mfma_f32_16x16x32_bf16 v[100:103], v[156:159], v[204:207], v[100:103]
	v_mfma_f32_16x16x32_bf16 v[92:95], v[164:167], v[204:207], v[92:95]
	v_mfma_f32_16x16x32_bf16 v[84:87], v[156:159], v[212:215], v[84:87]
	v_mfma_f32_16x16x32_bf16 v[76:79], v[164:167], v[212:215], v[76:79]
	s_setprio 0
	s_setprio 1
	v_mfma_f32_16x16x32_bf16 v[112:115], v[168:171], v[184:187], v[112:115]
	v_mfma_f32_16x16x32_bf16 v[104:107], v[176:179], v[184:187], v[104:107]
	v_mfma_f32_16x16x32_bf16 v[96:99], v[168:171], v[192:195], v[96:99]
	v_mfma_f32_16x16x32_bf16 v[88:91], v[176:179], v[192:195], v[88:91]
	v_mfma_f32_16x16x32_bf16 v[80:83], v[168:171], v[200:203], v[80:83]
	v_mfma_f32_16x16x32_bf16 v[72:75], v[176:179], v[200:203], v[72:75]
	v_mfma_f32_16x16x32_bf16 v[68:71], v[168:171], v[208:211], v[68:71]
	v_mfma_f32_16x16x32_bf16 v[64:67], v[176:179], v[208:211], v[64:67]
	v_mfma_f32_16x16x32_bf16 v[112:115], v[172:175], v[188:191], v[112:115]
	v_mfma_f32_16x16x32_bf16 v[104:107], v[180:183], v[188:191], v[104:107]
	v_mfma_f32_16x16x32_bf16 v[96:99], v[172:175], v[196:199], v[96:99]
	v_mfma_f32_16x16x32_bf16 v[88:91], v[180:183], v[196:199], v[88:91]
	v_mfma_f32_16x16x32_bf16 v[80:83], v[172:175], v[204:207], v[80:83]
	v_mfma_f32_16x16x32_bf16 v[72:75], v[180:183], v[204:207], v[72:75]
	v_mfma_f32_16x16x32_bf16 v[68:71], v[172:175], v[212:215], v[68:71]
	v_mfma_f32_16x16x32_bf16 v[64:67], v[180:183], v[212:215], v[64:67]
	s_setprio 0
	s_barrier
	s_add_i32 s42, s68, s45
	v_lshl_add_u64 v[144:145], v[144:145], 0, s[6:7]
	s_mov_b32 m0, s42
	ds_read_b128 v[184:187], v151 offset:49152
	ds_read_b128 v[188:191], v151 offset:50176
	ds_read_b128 v[192:195], v151 offset:51200
	ds_read_b128 v[196:199], v151 offset:52224
	ds_read_b128 v[200:203], v151 offset:53248
	ds_read_b128 v[204:207], v151 offset:54272
	ds_read_b128 v[208:211], v151 offset:55296
	ds_read_b128 v[212:215], v151 offset:56320
	global_load_lds_dwordx4 v[144:145], off
	s_add_i32 m0, s42, 0x2000
	s_add_u32 s40, s40, 0x40080
	v_lshl_add_u64 v[144:145], v[216:217], 0, s[6:7]
	s_addc_u32 s41, s41, 0
	s_add_i32 s42, s69, s45
	global_load_lds_dwordx4 v[144:145], off
	v_lshl_add_u64 v[144:145], s[40:41], 0, v[132:133]
	s_mov_b32 m0, s42
	s_nop 0
	global_load_lds_dwordx4 v[144:145], off
	v_lshl_add_u64 v[144:145], s[40:41], 0, v[128:129]
	s_add_i32 m0, s42, 0x2000
	s_nop 0
	global_load_lds_dwordx4 v[144:145], off
	v_lshl_add_u64 v[144:145], v[218:219], 0, s[6:7]
	s_mov_b32 m0, s54
	s_nop 0
	global_load_lds_dwordx4 v[144:145], off
	v_lshl_add_u64 v[144:145], v[220:221], 0, s[6:7]
	s_mov_b32 m0, s55
	s_nop 0
	global_load_lds_dwordx4 v[144:145], off
	s_waitcnt vmcnt(8)
	s_waitcnt lgkmcnt(0)
	s_barrier
	s_setprio 1
	s_waitcnt lgkmcnt(0)
	v_mfma_f32_16x16x32_bf16 v[60:63], v[152:155], v[184:187], v[60:63]
	v_mfma_f32_16x16x32_bf16 v[56:59], v[160:163], v[184:187], v[56:59]
	v_mfma_f32_16x16x32_bf16 v[52:55], v[152:155], v[192:195], v[52:55]
	v_mfma_f32_16x16x32_bf16 v[44:47], v[160:163], v[192:195], v[44:47]
	v_mfma_f32_16x16x32_bf16 v[36:39], v[152:155], v[200:203], v[36:39]
	v_mfma_f32_16x16x32_bf16 v[28:31], v[160:163], v[200:203], v[28:31]
	v_mfma_f32_16x16x32_bf16 v[20:23], v[152:155], v[208:211], v[20:23]
	v_mfma_f32_16x16x32_bf16 v[12:15], v[160:163], v[208:211], v[12:15]
	v_mfma_f32_16x16x32_bf16 v[60:63], v[156:159], v[188:191], v[60:63]
	v_mfma_f32_16x16x32_bf16 v[56:59], v[164:167], v[188:191], v[56:59]
	v_mfma_f32_16x16x32_bf16 v[52:55], v[156:159], v[196:199], v[52:55]
	v_mfma_f32_16x16x32_bf16 v[44:47], v[164:167], v[196:199], v[44:47]
	v_mfma_f32_16x16x32_bf16 v[36:39], v[156:159], v[204:207], v[36:39]
	v_mfma_f32_16x16x32_bf16 v[28:31], v[164:167], v[204:207], v[28:31]
	v_mfma_f32_16x16x32_bf16 v[20:23], v[156:159], v[212:215], v[20:23]
	v_mfma_f32_16x16x32_bf16 v[12:15], v[164:167], v[212:215], v[12:15]
	s_setprio 0
	s_setprio 1
	v_mfma_f32_16x16x32_bf16 v[48:51], v[168:171], v[184:187], v[48:51]
	v_mfma_f32_16x16x32_bf16 v[40:43], v[176:179], v[184:187], v[40:43]
	v_mfma_f32_16x16x32_bf16 v[32:35], v[168:171], v[192:195], v[32:35]
	v_mfma_f32_16x16x32_bf16 v[24:27], v[176:179], v[192:195], v[24:27]
	v_mfma_f32_16x16x32_bf16 v[16:19], v[168:171], v[200:203], v[16:19]
	v_mfma_f32_16x16x32_bf16 v[8:11], v[176:179], v[200:203], v[8:11]
	v_mfma_f32_16x16x32_bf16 v[4:7], v[168:171], v[208:211], v[4:7]
	v_mfma_f32_16x16x32_bf16 v[0:3], v[176:179], v[208:211], v[0:3]
	v_mfma_f32_16x16x32_bf16 v[48:51], v[172:175], v[188:191], v[48:51]
	v_mfma_f32_16x16x32_bf16 v[40:43], v[180:183], v[188:191], v[40:43]
	v_mfma_f32_16x16x32_bf16 v[32:35], v[172:175], v[196:199], v[32:35]
	v_mfma_f32_16x16x32_bf16 v[24:27], v[180:183], v[196:199], v[24:27]
	v_mfma_f32_16x16x32_bf16 v[16:19], v[172:175], v[204:207], v[16:19]
	v_mfma_f32_16x16x32_bf16 v[8:11], v[180:183], v[204:207], v[8:11]
	v_mfma_f32_16x16x32_bf16 v[4:7], v[172:175], v[212:215], v[4:7]
	v_mfma_f32_16x16x32_bf16 v[0:3], v[180:183], v[212:215], v[0:3]
	s_setprio 0
	s_barrier
	s_add_i32 s67, s67, 2
	s_add_u32 s30, s30, 0x100
	s_addc_u32 s31, s31, 0
	s_add_u32 s65, s65, 0x100
	s_addc_u32 s66, s66, 0
	s_cmp_gt_u32 s67, 13
	s_cbranch_scc0 .LBB0_1726
	s_and_b64 vcc, exec, s[8:9]
	s_cbranch_vccz .LBB0_1729
	s_barrier
.LBB0_1729:
	s_ashr_i32 s21, s62, 31
	s_lshr_b32 s21, s21, 28
	s_add_i32 s21, s62, s21
	s_ashr_i32 s30, s21, 4
	s_ashr_i32 s31, s30, 31
	s_lshl_b32 s19, s62, 8
	s_lshl_b64 s[40:41], s[30:31], 25
	s_add_u32 s40, s51, s40
	s_addc_u32 s41, s52, s41
	s_lshl_b32 s21, s30, 12
	s_sub_i32 s19, s19, s21
	v_lshl_add_u32 v152, s28, 8, v146
	v_or_b32_e32 v144, s19, v148
	v_ashrrev_i32_e32 v145, 31, v144
	v_ashrrev_i32_e32 v153, 31, v152
	v_lshl_add_u64 v[154:155], v[144:145], 1, s[40:41]
	v_lshlrev_b64 v[144:145], 13, v[152:153]
	v_lshl_add_u64 v[144:145], v[154:155], 0, v[144:145]
	v_cvt_pk_bf16_f32 v124, v124, v125
	v_cvt_pk_bf16_f32 v125, v126, v127
	v_cvt_pk_bf16_f32 v126, v120, v121
	v_cvt_pk_bf16_f32 v127, v122, v123
	v_cvt_pk_bf16_f32 v112, v112, v113
	v_cvt_pk_bf16_f32 v113, v114, v115
	v_cvt_pk_bf16_f32 v114, v104, v105
	v_or_b32_e32 v104, 16, v152
	v_ashrrev_i32_e32 v105, 31, v104
	v_lshlrev_b64 v[104:105], 13, v[104:105]
	v_cvt_pk_bf16_f32 v115, v106, v107
	v_mov_b32_e32 v228, v112
	v_mov_b32_e32 v229, v113
	v_mov_b32_e32 v230, v114
	v_mov_b32_e32 v231, v115
	v_lshl_add_u64 v[226:227], v[144:145], 0, s[98:99]
	v_mov_b32_dpp v112, v124 row_ror:8 row_mask:0xf bank_mask:0x3
	v_mov_b32_dpp v113, v125 row_ror:8 row_mask:0xf bank_mask:0x3
	v_mov_b32_dpp v114, v126 row_ror:8 row_mask:0xf bank_mask:0x3
	v_mov_b32_dpp v115, v127 row_ror:8 row_mask:0xf bank_mask:0x3
	v_mov_b32_dpp v124, v228 row_ror:8 row_mask:0xf bank_mask:0xc
	v_mov_b32_dpp v125, v229 row_ror:8 row_mask:0xf bank_mask:0xc
	v_mov_b32_dpp v126, v230 row_ror:8 row_mask:0xf bank_mask:0xc
	v_mov_b32_dpp v127, v231 row_ror:8 row_mask:0xf bank_mask:0xc
	global_store_dwordx4 v[144:145], v[124:127], off nt
	global_store_dwordx4 v[226:227], v[112:115], off nt
	s_nop 1
	v_lshl_add_u64 v[112:113], v[154:155], 0, v[104:105]
	v_cvt_pk_bf16_f32 v104, v116, v117
	v_cvt_pk_bf16_f32 v105, v118, v119
	v_cvt_pk_bf16_f32 v106, v108, v109
	v_cvt_pk_bf16_f32 v107, v110, v111
	v_cvt_pk_bf16_f32 v96, v96, v97
	v_cvt_pk_bf16_f32 v97, v98, v99
	v_cvt_pk_bf16_f32 v98, v88, v89
	v_or_b32_e32 v88, 32, v152
	v_ashrrev_i32_e32 v89, 31, v88
	v_lshlrev_b64 v[88:89], 13, v[88:89]
	v_cvt_pk_bf16_f32 v99, v90, v91
	v_mov_b32_e32 v228, v96
	v_mov_b32_e32 v229, v97
	v_mov_b32_e32 v230, v98
	v_mov_b32_e32 v231, v99
	v_lshl_add_u64 v[226:227], v[112:113], 0, s[98:99]
	v_mov_b32_dpp v96, v104 row_ror:8 row_mask:0xf bank_mask:0x3
	v_mov_b32_dpp v97, v105 row_ror:8 row_mask:0xf bank_mask:0x3
	v_mov_b32_dpp v98, v106 row_ror:8 row_mask:0xf bank_mask:0x3
	v_mov_b32_dpp v99, v107 row_ror:8 row_mask:0xf bank_mask:0x3
	v_mov_b32_dpp v104, v228 row_ror:8 row_mask:0xf bank_mask:0xc
	v_mov_b32_dpp v105, v229 row_ror:8 row_mask:0xf bank_mask:0xc
	v_mov_b32_dpp v106, v230 row_ror:8 row_mask:0xf bank_mask:0xc
	v_mov_b32_dpp v107, v231 row_ror:8 row_mask:0xf bank_mask:0xc
	global_store_dwordx4 v[112:113], v[104:107], off nt
	global_store_dwordx4 v[226:227], v[96:99], off nt
	s_nop 1
	v_lshl_add_u64 v[96:97], v[154:155], 0, v[88:89]
	v_cvt_pk_bf16_f32 v88, v100, v101
	v_cvt_pk_bf16_f32 v89, v102, v103
	v_cvt_pk_bf16_f32 v90, v92, v93
	v_cvt_pk_bf16_f32 v91, v94, v95
	v_cvt_pk_bf16_f32 v80, v80, v81
	v_cvt_pk_bf16_f32 v81, v82, v83
	v_cvt_pk_bf16_f32 v82, v72, v73
	v_or_b32_e32 v72, 48, v152
	v_ashrrev_i32_e32 v73, 31, v72
	v_lshlrev_b64 v[72:73], 13, v[72:73]
	v_cvt_pk_bf16_f32 v83, v74, v75
	v_mov_b32_e32 v228, v80
	v_mov_b32_e32 v229, v81
	v_mov_b32_e32 v230, v82
	v_mov_b32_e32 v231, v83
	v_lshl_add_u64 v[226:227], v[96:97], 0, s[98:99]
	v_mov_b32_dpp v80, v88 row_ror:8 row_mask:0xf bank_mask:0x3
	v_mov_b32_dpp v81, v89 row_ror:8 row_mask:0xf bank_mask:0x3
	v_mov_b32_dpp v82, v90 row_ror:8 row_mask:0xf bank_mask:0x3
	v_mov_b32_dpp v83, v91 row_ror:8 row_mask:0xf bank_mask:0x3
	v_mov_b32_dpp v88, v228 row_ror:8 row_mask:0xf bank_mask:0xc
	v_mov_b32_dpp v89, v229 row_ror:8 row_mask:0xf bank_mask:0xc
	v_mov_b32_dpp v90, v230 row_ror:8 row_mask:0xf bank_mask:0xc
	v_mov_b32_dpp v91, v231 row_ror:8 row_mask:0xf bank_mask:0xc
	global_store_dwordx4 v[96:97], v[88:91], off nt
	global_store_dwordx4 v[226:227], v[80:83], off nt
	s_nop 1
	v_lshl_add_u64 v[80:81], v[154:155], 0, v[72:73]
	v_cvt_pk_bf16_f32 v72, v84, v85
	v_cvt_pk_bf16_f32 v73, v86, v87
	v_cvt_pk_bf16_f32 v74, v76, v77
	v_cvt_pk_bf16_f32 v75, v78, v79
	v_cvt_pk_bf16_f32 v68, v68, v69
	v_cvt_pk_bf16_f32 v69, v70, v71
	v_cvt_pk_bf16_f32 v70, v64, v65
	v_cvt_pk_bf16_f32 v71, v66, v67
	v_mov_b32_e32 v228, v68
	v_mov_b32_e32 v229, v69
	v_mov_b32_e32 v230, v70
	v_mov_b32_e32 v231, v71
	v_lshl_add_u64 v[226:227], v[80:81], 0, s[98:99]
	v_mov_b32_dpp v68, v72 row_ror:8 row_mask:0xf bank_mask:0x3
	v_mov_b32_dpp v69, v73 row_ror:8 row_mask:0xf bank_mask:0x3
	v_mov_b32_dpp v70, v74 row_ror:8 row_mask:0xf bank_mask:0x3
	v_mov_b32_dpp v71, v75 row_ror:8 row_mask:0xf bank_mask:0x3
	v_mov_b32_dpp v72, v228 row_ror:8 row_mask:0xf bank_mask:0xc
	v_mov_b32_dpp v73, v229 row_ror:8 row_mask:0xf bank_mask:0xc
	v_mov_b32_dpp v74, v230 row_ror:8 row_mask:0xf bank_mask:0xc
	v_mov_b32_dpp v75, v231 row_ror:8 row_mask:0xf bank_mask:0xc
	global_store_dwordx4 v[80:81], v[72:75], off nt
	global_store_dwordx4 v[226:227], v[68:71], off nt
	v_cvt_pk_bf16_f32 v60, v60, v61
	v_cvt_pk_bf16_f32 v61, v62, v63
	v_cvt_pk_bf16_f32 v62, v56, v57
	v_add_co_u32_e32 v56, vcc, s58, v144
	v_lshl_add_u64 v[64:65], v[144:145], 0, s[10:11]
	s_nop 0
	v_addc_co_u32_e32 v57, vcc, 0, v145, vcc
	v_cvt_pk_bf16_f32 v63, v58, v59
	v_cvt_pk_bf16_f32 v48, v48, v49
	v_cvt_pk_bf16_f32 v49, v50, v51
	v_cvt_pk_bf16_f32 v50, v40, v41
	v_cvt_pk_bf16_f32 v51, v42, v43
	v_mov_b32_e32 v228, v48
	v_mov_b32_e32 v229, v49
	v_mov_b32_e32 v230, v50
	v_mov_b32_e32 v231, v51
	v_lshl_add_u64 v[226:227], v[64:65], 0, s[98:99]
	v_mov_b32_dpp v48, v60 row_ror:8 row_mask:0xf bank_mask:0x3
	v_mov_b32_dpp v49, v61 row_ror:8 row_mask:0xf bank_mask:0x3
	v_mov_b32_dpp v50, v62 row_ror:8 row_mask:0xf bank_mask:0x3
	v_mov_b32_dpp v51, v63 row_ror:8 row_mask:0xf bank_mask:0x3
	v_mov_b32_dpp v60, v228 row_ror:8 row_mask:0xf bank_mask:0xc
	v_mov_b32_dpp v61, v229 row_ror:8 row_mask:0xf bank_mask:0xc
	v_mov_b32_dpp v62, v230 row_ror:8 row_mask:0xf bank_mask:0xc
	v_mov_b32_dpp v63, v231 row_ror:8 row_mask:0xf bank_mask:0xc
	global_store_dwordx4 v[56:57], v[60:63], off nt
	global_store_dwordx4 v[226:227], v[48:51], off nt
	v_cvt_pk_bf16_f32 v40, v52, v53
	v_cvt_pk_bf16_f32 v41, v54, v55
	v_cvt_pk_bf16_f32 v42, v44, v45
	v_add_co_u32_e32 v44, vcc, s59, v144
	s_nop 0
	v_lshl_add_u64 v[48:49], v[144:145], 0, s[12:13]
	v_addc_co_u32_e32 v45, vcc, 0, v145, vcc
	v_cvt_pk_bf16_f32 v43, v46, v47
	v_cvt_pk_bf16_f32 v32, v32, v33
	v_cvt_pk_bf16_f32 v33, v34, v35
	v_cvt_pk_bf16_f32 v34, v24, v25
	v_cvt_pk_bf16_f32 v35, v26, v27
	v_mov_b32_e32 v228, v32
	v_mov_b32_e32 v229, v33
	v_mov_b32_e32 v230, v34
	v_mov_b32_e32 v231, v35
	v_lshl_add_u64 v[226:227], v[48:49], 0, s[98:99]
	v_mov_b32_dpp v32, v40 row_ror:8 row_mask:0xf bank_mask:0x3
	v_mov_b32_dpp v33, v41 row_ror:8 row_mask:0xf bank_mask:0x3
	v_mov_b32_dpp v34, v42 row_ror:8 row_mask:0xf bank_mask:0x3
	v_mov_b32_dpp v35, v43 row_ror:8 row_mask:0xf bank_mask:0x3
	v_mov_b32_dpp v40, v228 row_ror:8 row_mask:0xf bank_mask:0xc
	v_mov_b32_dpp v41, v229 row_ror:8 row_mask:0xf bank_mask:0xc
	v_mov_b32_dpp v42, v230 row_ror:8 row_mask:0xf bank_mask:0xc
	v_mov_b32_dpp v43, v231 row_ror:8 row_mask:0xf bank_mask:0xc
	global_store_dwordx4 v[44:45], v[40:43], off nt
	global_store_dwordx4 v[226:227], v[32:35], off nt
	v_cvt_pk_bf16_f32 v24, v36, v37
	v_cvt_pk_bf16_f32 v25, v38, v39
	v_cvt_pk_bf16_f32 v26, v28, v29
	v_add_co_u32_e32 v28, vcc, s60, v144
	s_nop 0
	v_lshl_add_u64 v[32:33], v[144:145], 0, s[14:15]
	v_addc_co_u32_e32 v29, vcc, 0, v145, vcc
	v_cvt_pk_bf16_f32 v27, v30, v31
	v_cvt_pk_bf16_f32 v16, v16, v17
	v_cvt_pk_bf16_f32 v17, v18, v19
	v_cvt_pk_bf16_f32 v18, v8, v9
	v_cvt_pk_bf16_f32 v19, v10, v11
	v_mov_b32_e32 v228, v16
	v_mov_b32_e32 v229, v17
	v_mov_b32_e32 v230, v18
	v_mov_b32_e32 v231, v19
	v_lshl_add_u64 v[226:227], v[32:33], 0, s[98:99]
	v_mov_b32_dpp v16, v24 row_ror:8 row_mask:0xf bank_mask:0x3
	v_mov_b32_dpp v17, v25 row_ror:8 row_mask:0xf bank_mask:0x3
	v_mov_b32_dpp v18, v26 row_ror:8 row_mask:0xf bank_mask:0x3
	v_mov_b32_dpp v19, v27 row_ror:8 row_mask:0xf bank_mask:0x3
	v_mov_b32_dpp v24, v228 row_ror:8 row_mask:0xf bank_mask:0xc
	v_mov_b32_dpp v25, v229 row_ror:8 row_mask:0xf bank_mask:0xc
	v_mov_b32_dpp v26, v230 row_ror:8 row_mask:0xf bank_mask:0xc
	v_mov_b32_dpp v27, v231 row_ror:8 row_mask:0xf bank_mask:0xc
	global_store_dwordx4 v[28:29], v[24:27], off nt
	global_store_dwordx4 v[226:227], v[16:19], off nt
	v_cvt_pk_bf16_f32 v8, v20, v21
	v_cvt_pk_bf16_f32 v9, v22, v23
	v_cvt_pk_bf16_f32 v10, v12, v13
	v_add_co_u32_e32 v12, vcc, s61, v144
	s_nop 0
	v_lshl_add_u64 v[16:17], v[144:145], 0, s[16:17]
	v_addc_co_u32_e32 v13, vcc, 0, v145, vcc
	s_andn2_b64 vcc, exec, s[0:1]
	s_mov_b64 s[0:1], -1
	v_cvt_pk_bf16_f32 v11, v14, v15
	v_cvt_pk_bf16_f32 v4, v4, v5
	v_cvt_pk_bf16_f32 v5, v6, v7
	v_cvt_pk_bf16_f32 v6, v0, v1
	v_cvt_pk_bf16_f32 v7, v2, v3
	v_mov_b32_e32 v228, v4
	v_mov_b32_e32 v229, v5
	v_mov_b32_e32 v230, v6
	v_mov_b32_e32 v231, v7
	v_lshl_add_u64 v[226:227], v[16:17], 0, s[98:99]
	v_mov_b32_dpp v4, v8 row_ror:8 row_mask:0xf bank_mask:0x3
	v_mov_b32_dpp v5, v9 row_ror:8 row_mask:0xf bank_mask:0x3
	v_mov_b32_dpp v6, v10 row_ror:8 row_mask:0xf bank_mask:0x3
	v_mov_b32_dpp v7, v11 row_ror:8 row_mask:0xf bank_mask:0x3
	v_mov_b32_dpp v8, v228 row_ror:8 row_mask:0xf bank_mask:0xc
	v_mov_b32_dpp v9, v229 row_ror:8 row_mask:0xf bank_mask:0xc
	v_mov_b32_dpp v10, v230 row_ror:8 row_mask:0xf bank_mask:0xc
	v_mov_b32_dpp v11, v231 row_ror:8 row_mask:0xf bank_mask:0xc
	global_store_dwordx4 v[12:13], v[8:11], off nt
	global_store_dwordx4 v[226:227], v[4:7], off nt
	s_cbranch_vccnz .LBB0_1718
	s_andn2_b64 vcc, exec, s[4:5]
	s_cbranch_vccnz .LBB0_1717
	s_barrier
	s_branch .LBB0_1717
